# mix0 spatial-gating item loop: MFMA A fragments, bias and the 32 two-byte u values loaded at the top of the item instead of one dependent global round trip per k-step / output row
# speedup vs baseline: 1.0384x; 1.0009x over previous
; #define LAS __attribute__((address_space(3)))
; __device__ __forceinline__ void phase_mix0(const Params& p, LAS unsigned char* lds) {
;     ...
;         for (int q = 0; q < 4; ++q) { const int pc = tid + 512 * q, j = pc >> 4, d8 = (pc & 15) * 8;
;             const h16x8 v = *(const h16x8*)(V + (size_t)(t0 + j) * 1024 + g * 128 + d8);
;             const float mu = ST[2 * (t0 + j)] * (1.f / 1024.f), rs = rsqrtf(fmaxf(ST[2 * (t0 + j) + 1] * (1.f / 1024.f) - mu * mu, 0.f) + 1e-5f);
; #pragma unroll
;             for (int e = 0; e < 8; ++e) vnT[(d8 + e) * 136 + ((((j >> 3) ^ (pc & 15)) << 3) | (j & 7))] = (h16)(((float)v[e] - mu) * rs * lng[g * 128 + d8 + e] + lnb[g * 128 + d8 + e]); }
;         __syncthreads();
;         const int itile = wave >> 1, dt0 = (wave & 1) * 2;
;         f32x16 acc0, acc1;
; #pragma unroll
;         for (int e = 0; e < 16; ++e) { acc0[e] = 0.f; acc1[e] = 0.f; }
;         const h16* Arow = WSH + ((size_t)g * 128 + itile * 32 + (lane & 31)) * 128 + 8 * (lane >> 5);
;         const int d0_ = dt0 * 32 + (lane & 31), d1_ = d0_ + 32;
;         const LAS h16* B0p = vnT + d0_ * 136; const LAS h16* B1p = vnT + d1_ * 136;
; #pragma unroll
;         for (int ks = 0; ks < 8; ++ks) {
;             const h16x8 a = *(const h16x8*)(Arow + 16 * ks);
;             const int jg = 2 * ks + (lane >> 5);
;             const h16x8 b0 = *(const LAS h16x8*)(B0p + ((jg ^ ((d0_ >> 3) & 15)) << 3)), b1 = *(const LAS h16x8*)(B1p + ((jg ^ ((d1_ >> 3) & 15)) << 3));
;             acc0 = __builtin_amdgcn_mfma_f32_32x32x16_f16(a, b0, acc0, 0, 0, 0);
;             acc1 = __builtin_amdgcn_mfma_f32_32x32x16_f16(a, b1, acc1, 0, 0, 0);
;         }
; #pragma unroll
;         for (int r = 0; r < 16; ++r) { const int i = itile * 32 + (r & 3) + 8 * (r >> 2) + 4 * (lane >> 5); const size_t t = (size_t)(t0 + i);
;             const float bias = bs[g * 128 + i];
;             const int d0 = g * 128 + dt0 * 32 + (lane & 31);
;             YC[t * 2048 + 1024 + d0] = (h16)((acc0[r] + bias) * (float)U[t * 1024 + d0]);
;             YC[t * 2048 + 1024 + d0 + 32] = (h16)((acc1[r] + bias) * (float)U[t * 1024 + d0 + 32]); }
.LBB0_289:
	s_and_b32 s48, s29, 0xffffff80
	s_and_b32 s14, s23, 0x380
	v_or_b32_e32 v0, s48, v46
	v_or_b32_e32 v16, s48, v47
	v_or_b32_e32 v18, s48, v48
	v_add_u32_e32 v20, s48, v49
	s_lshl_b32 s20, s14, 1
	v_ashrrev_i32_e32 v1, 31, v0
	v_lshlrev_b32_e32 v24, 1, v0
	v_ashrrev_i32_e32 v17, 31, v16
	v_lshlrev_b32_e32 v26, 1, v16
	v_ashrrev_i32_e32 v19, 31, v18
	v_lshlrev_b32_e32 v28, 1, v18
	v_lshlrev_b32_e32 v30, 1, v20
	v_or_b32_e32 v2, s14, v42
	v_lshl_add_u64 v[22:23], v[34:35], 0, s[20:21]
	v_ashrrev_i32_e32 v21, 31, v20
	v_lshlrev_b64 v[40:41], 11, v[0:1]
	v_ashrrev_i32_e32 v25, 31, v24
	v_lshlrev_b64 v[16:17], 11, v[16:17]
	v_ashrrev_i32_e32 v27, 31, v26
	v_lshlrev_b64 v[18:19], 11, v[18:19]
	v_ashrrev_i32_e32 v29, 31, v28
	v_ashrrev_i32_e32 v31, 31, v30
	v_lshlrev_b32_e32 v12, 2, v2
	v_lshlrev_b64 v[20:21], 11, v[20:21]
	v_lshl_add_u64 v[40:41], v[22:23], 0, v[40:41]
	v_lshl_add_u64 v[24:25], v[24:25], 2, s[18:19]
	v_lshl_add_u64 v[86:87], v[22:23], 0, v[16:17]
	v_lshl_add_u64 v[26:27], v[26:27], 2, s[18:19]
	v_lshl_add_u64 v[88:89], v[22:23], 0, v[18:19]
	v_lshl_add_u64 v[28:29], v[28:29], 2, s[18:19]
	v_lshl_add_u64 v[30:31], v[30:31], 2, s[18:19]
	s_waitcnt vmcnt(0)
	s_barrier
	global_load_dwordx4 v[0:3], v12, s[24:25] offset:16
	global_load_dwordx4 v[4:7], v12, s[26:27] offset:16
	global_load_dwordx4 v[8:11], v12, s[24:25]
	s_nop 0
	global_load_dwordx4 v[12:15], v12, s[26:27]
	v_lshl_add_u64 v[90:91], v[22:23], 0, v[20:21]
	global_load_dwordx2 v[92:93], v[24:25], off
	global_load_dwordx4 v[16:19], v[40:41], off
	s_nop 0
	global_load_dwordx2 v[40:41], v[26:27], off
	global_load_dwordx4 v[20:23], v[86:87], off
	s_nop 0
	global_load_dwordx2 v[86:87], v[28:29], off
	global_load_dwordx4 v[24:27], v[88:89], off
	s_nop 0
	global_load_dwordx2 v[88:89], v[30:31], off
	s_nop 0
	global_load_dwordx4 v[28:31], v[90:91], off
	v_add_lshl_u32 v32, v43, s14, 8
	v_lshl_add_u64 v[38:39], v[36:37], 0, v[32:33]
	global_load_dwordx4 v[132:135], v[38:39], off
	global_load_dwordx4 v[136:139], v[38:39], off offset:32
	global_load_dwordx4 v[140:143], v[38:39], off offset:64
	global_load_dwordx4 v[144:147], v[38:39], off offset:96
	global_load_dwordx4 v[148:151], v[38:39], off offset:128
	global_load_dwordx4 v[152:155], v[38:39], off offset:160
	global_load_dwordx4 v[156:159], v[38:39], off offset:192
	global_load_dwordx4 v[160:163], v[38:39], off offset:224
	v_add_lshl_u32 v212, s14, v45, 2
	global_load_dwordx4 v[110:113], v212, s[30:31]
	global_load_dwordx4 v[114:117], v212, s[30:31] offset:32
	global_load_dwordx4 v[118:121], v212, s[30:31] offset:64
	global_load_dwordx4 v[122:125], v212, s[30:31] offset:96
	v_or_b32_e32 v202, s14, v44
	v_lshlrev_b32_e32 v202, 1, v202
	v_mov_b32_e32 v203, 0
	v_lshl_add_u64 v[204:205], s[12:13], 0, v[202:203]
	v_add_u32_e32 v206, s48, v45
	v_ashrrev_i32_e32 v207, 31, v206
	v_lshlrev_b64 v[208:209], 11, v[206:207]
	v_lshl_add_u64 v[208:209], v[204:205], 0, v[208:209]
	global_load_ushort v170, v[208:209], off
	s_nop 0
	global_load_ushort v171, v[208:209], off offset:64
	v_add_u32_e32 v210, s48, v66
	v_ashrrev_i32_e32 v211, 31, v210
	v_lshlrev_b64 v[212:213], 11, v[210:211]
	v_lshl_add_u64 v[212:213], v[204:205], 0, v[212:213]
	global_load_ushort v172, v[212:213], off
	s_nop 0
	global_load_ushort v173, v[212:213], off offset:64
	v_add_u32_e32 v206, s48, v67
	v_ashrrev_i32_e32 v207, 31, v206
	v_lshlrev_b64 v[208:209], 11, v[206:207]
	v_lshl_add_u64 v[208:209], v[204:205], 0, v[208:209]
	global_load_ushort v174, v[208:209], off
	s_nop 0
	global_load_ushort v175, v[208:209], off offset:64
	v_add_u32_e32 v210, s48, v68
	v_ashrrev_i32_e32 v211, 31, v210
	v_lshlrev_b64 v[212:213], 11, v[210:211]
	v_lshl_add_u64 v[212:213], v[204:205], 0, v[212:213]
	global_load_ushort v176, v[212:213], off
	s_nop 0
	global_load_ushort v177, v[212:213], off offset:64
	v_add_u32_e32 v206, s48, v69
	v_ashrrev_i32_e32 v207, 31, v206
	v_lshlrev_b64 v[208:209], 11, v[206:207]
	v_lshl_add_u64 v[208:209], v[204:205], 0, v[208:209]
	global_load_ushort v178, v[208:209], off
	s_nop 0
	global_load_ushort v179, v[208:209], off offset:64
	v_add_u32_e32 v210, s48, v70
	v_ashrrev_i32_e32 v211, 31, v210
	v_lshlrev_b64 v[212:213], 11, v[210:211]
	v_lshl_add_u64 v[212:213], v[204:205], 0, v[212:213]
	global_load_ushort v180, v[212:213], off
	s_nop 0
	global_load_ushort v181, v[212:213], off offset:64
	v_add_u32_e32 v206, s48, v71
	v_ashrrev_i32_e32 v207, 31, v206
	v_lshlrev_b64 v[208:209], 11, v[206:207]
	v_lshl_add_u64 v[208:209], v[204:205], 0, v[208:209]
	global_load_ushort v182, v[208:209], off
	s_nop 0
	global_load_ushort v183, v[208:209], off offset:64
	v_add_u32_e32 v210, s48, v72
	v_ashrrev_i32_e32 v211, 31, v210
	v_lshlrev_b64 v[212:213], 11, v[210:211]
	v_lshl_add_u64 v[212:213], v[204:205], 0, v[212:213]
	global_load_ushort v184, v[212:213], off
	s_nop 0
	global_load_ushort v185, v[212:213], off offset:64
	v_add_u32_e32 v206, s48, v73
	v_ashrrev_i32_e32 v207, 31, v206
	v_lshlrev_b64 v[208:209], 11, v[206:207]
	v_lshl_add_u64 v[208:209], v[204:205], 0, v[208:209]
	global_load_ushort v186, v[208:209], off
	s_nop 0
	global_load_ushort v187, v[208:209], off offset:64
	v_add_u32_e32 v210, s48, v74
	v_ashrrev_i32_e32 v211, 31, v210
	v_lshlrev_b64 v[212:213], 11, v[210:211]
	v_lshl_add_u64 v[212:213], v[204:205], 0, v[212:213]
	global_load_ushort v188, v[212:213], off
	s_nop 0
	global_load_ushort v189, v[212:213], off offset:64
	v_add_u32_e32 v206, s48, v75
	v_ashrrev_i32_e32 v207, 31, v206
	v_lshlrev_b64 v[208:209], 11, v[206:207]
	v_lshl_add_u64 v[208:209], v[204:205], 0, v[208:209]
	global_load_ushort v190, v[208:209], off
	s_nop 0
; __device__ __forceinline__ void phase_mix0(const Params& p, LAS unsigned char* lds) {
;     ...
;         for (int q = 0; q < 4; ++q) { const int pc = tid + 512 * q, j = pc >> 4, d8 = (pc & 15) * 8;
;             const h16x8 v = *(const h16x8*)(V + (size_t)(t0 + j) * 1024 + g * 128 + d8);
;             const float mu = ST[2 * (t0 + j)] * (1.f / 1024.f), rs = rsqrtf(fmaxf(ST[2 * (t0 + j) + 1] * (1.f / 1024.f) - mu * mu, 0.f) + 1e-5f);
; #pragma unroll
;             for (int e = 0; e < 8; ++e) vnT[(d8 + e) * 136 + ((((j >> 3) ^ (pc & 15)) << 3) | (j & 7))] = (h16)(((float)v[e] - mu) * rs * lng[g * 128 + d8 + e] + lnb[g * 128 + d8 + e]); }
;     ...
;         for (int r = 0; r < 16; ++r) { const int i = itile * 32 + (r & 3) + 8 * (r >> 2) + 4 * (lane >> 5); const size_t t = (size_t)(t0 + i);
;             const float bias = bs[g * 128 + i];
;             const int d0 = g * 128 + dt0 * 32 + (lane & 31);
;             YC[t * 2048 + 1024 + d0] = (h16)((acc0[r] + bias) * (float)U[t * 1024 + d0]);
;             YC[t * 2048 + 1024 + d0 + 32] = (h16)((acc1[r] + bias) * (float)U[t * 1024 + d0 + 32]); }
	global_load_ushort v191, v[208:209], off offset:64
	v_add_u32_e32 v210, s48, v76
	v_ashrrev_i32_e32 v211, 31, v210
	v_lshlrev_b64 v[212:213], 11, v[210:211]
	v_lshl_add_u64 v[212:213], v[204:205], 0, v[212:213]
	global_load_ushort v192, v[212:213], off
	s_nop 0
	global_load_ushort v193, v[212:213], off offset:64
	v_add_u32_e32 v206, s48, v77
	v_ashrrev_i32_e32 v207, 31, v206
	v_lshlrev_b64 v[208:209], 11, v[206:207]
	v_lshl_add_u64 v[208:209], v[204:205], 0, v[208:209]
	global_load_ushort v194, v[208:209], off
	s_nop 0
	global_load_ushort v195, v[208:209], off offset:64
	v_add_u32_e32 v210, s48, v78
	v_ashrrev_i32_e32 v211, 31, v210
	v_lshlrev_b64 v[212:213], 11, v[210:211]
	v_lshl_add_u64 v[212:213], v[204:205], 0, v[212:213]
	global_load_ushort v196, v[212:213], off
	s_nop 0
	global_load_ushort v197, v[212:213], off offset:64
	v_add_u32_e32 v206, s48, v79
	v_ashrrev_i32_e32 v207, 31, v206
	v_lshlrev_b64 v[208:209], 11, v[206:207]
	v_lshl_add_u64 v[208:209], v[204:205], 0, v[208:209]
	global_load_ushort v198, v[208:209], off
	s_nop 0
	global_load_ushort v199, v[208:209], off offset:64
	v_add_u32_e32 v210, s48, v80
	v_ashrrev_i32_e32 v211, 31, v210
	v_lshlrev_b64 v[212:213], 11, v[210:211]
	v_lshl_add_u64 v[212:213], v[204:205], 0, v[212:213]
	global_load_ushort v200, v[212:213], off
	s_nop 0
	global_load_ushort v201, v[212:213], off offset:64
	s_add_i32 s47, s47, s74
	s_add_i32 s29, s29, s33
	s_waitcnt vmcnt(51)
	v_pk_mul_f32 v[90:91], v[92:93], s[22:23] op_sel_hi:[1,0]
	s_waitcnt vmcnt(50)
	v_cvt_f32_f16_e32 v32, v16
	v_cvt_f32_f16_sdwa v85, v16 dst_sel:DWORD dst_unused:UNUSED_PAD src0_sel:WORD_1
	v_cvt_f32_f16_e32 v92, v17
	v_cvt_f32_f16_sdwa v93, v17 dst_sel:DWORD dst_unused:UNUSED_PAD src0_sel:WORD_1
	v_cvt_f32_f16_e32 v94, v18
	v_cvt_f32_f16_sdwa v95, v18 dst_sel:DWORD dst_unused:UNUSED_PAD src0_sel:WORD_1
	v_cvt_f32_f16_e32 v96, v19
	v_cvt_f32_f16_sdwa v97, v19 dst_sel:DWORD dst_unused:UNUSED_PAD src0_sel:WORD_1
	s_waitcnt vmcnt(49)
	v_pk_mul_f32 v[16:17], v[40:41], s[22:23] op_sel_hi:[1,0]
	s_waitcnt vmcnt(48)
	v_cvt_f32_f16_e32 v40, v20
	v_cvt_f32_f16_sdwa v41, v20 dst_sel:DWORD dst_unused:UNUSED_PAD src0_sel:WORD_1
	v_cvt_f32_f16_e32 v98, v21
	v_cvt_f32_f16_sdwa v99, v21 dst_sel:DWORD dst_unused:UNUSED_PAD src0_sel:WORD_1
	v_cvt_f32_f16_e32 v100, v22
	v_cvt_f32_f16_sdwa v22, v22 dst_sel:DWORD dst_unused:UNUSED_PAD src0_sel:WORD_1
	v_cvt_f32_f16_e32 v101, v23
	v_cvt_f32_f16_sdwa v23, v23 dst_sel:DWORD dst_unused:UNUSED_PAD src0_sel:WORD_1
	s_waitcnt vmcnt(47)
	v_pk_mul_f32 v[18:19], v[86:87], s[22:23] op_sel_hi:[1,0]
	s_waitcnt vmcnt(46)
	v_cvt_f32_f16_e32 v86, v24
	v_cvt_f32_f16_sdwa v24, v24 dst_sel:DWORD dst_unused:UNUSED_PAD src0_sel:WORD_1
	v_cvt_f32_f16_e32 v87, v25
	v_cvt_f32_f16_sdwa v25, v25 dst_sel:DWORD dst_unused:UNUSED_PAD src0_sel:WORD_1
	v_cvt_f32_f16_e32 v102, v26
	v_cvt_f32_f16_sdwa v26, v26 dst_sel:DWORD dst_unused:UNUSED_PAD src0_sel:WORD_1
	v_cvt_f32_f16_e32 v103, v27
	v_cvt_f32_f16_sdwa v27, v27 dst_sel:DWORD dst_unused:UNUSED_PAD src0_sel:WORD_1
	s_waitcnt vmcnt(45)
	v_pk_mul_f32 v[20:21], v[88:89], s[22:23] op_sel_hi:[1,0]
	s_waitcnt vmcnt(44)
	v_cvt_f32_f16_e32 v88, v28
	v_cvt_f32_f16_sdwa v28, v28 dst_sel:DWORD dst_unused:UNUSED_PAD src0_sel:WORD_1
	v_cvt_f32_f16_e32 v89, v29
	v_cvt_f32_f16_sdwa v29, v29 dst_sel:DWORD dst_unused:UNUSED_PAD src0_sel:WORD_1
	v_cvt_f32_f16_e32 v104, v30
	v_cvt_f32_f16_sdwa v30, v30 dst_sel:DWORD dst_unused:UNUSED_PAD src0_sel:WORD_1
	v_cvt_f32_f16_e32 v105, v31
	v_cvt_f32_f16_sdwa v31, v31 dst_sel:DWORD dst_unused:UNUSED_PAD src0_sel:WORD_1
	v_fma_f32 v91, -v90, v90, v91
	v_fma_f32 v17, -v16, v16, v17
	v_fma_f32 v19, -v18, v18, v19
	v_fma_f32 v21, -v20, v20, v21
	v_max_f32_e32 v91, 0, v91
	v_max_f32_e32 v17, 0, v17
	v_max_f32_e32 v19, 0, v19
	v_max_f32_e32 v21, 0, v21
	v_add_f32_e32 v91, 0x3727c5ac, v91
	v_add_f32_e32 v17, 0x3727c5ac, v17
	v_add_f32_e32 v19, 0x3727c5ac, v19
	v_add_f32_e32 v21, 0x3727c5ac, v21
	v_mul_f32_e32 v106, 0x4b800000, v91
	v_sub_f32_e32 v32, v32, v90
	v_sub_f32_e32 v85, v85, v90
	v_sub_f32_e32 v92, v92, v90
	v_sub_f32_e32 v93, v93, v90
	v_sub_f32_e32 v94, v94, v90
	v_sub_f32_e32 v95, v95, v90
	v_sub_f32_e32 v96, v96, v90
	v_sub_f32_e32 v90, v97, v90
	v_mul_f32_e32 v97, 0x4b800000, v17
	v_cmp_gt_f32_e32 vcc, s46, v17
	v_sub_f32_e32 v40, v40, v16
	v_sub_f32_e32 v41, v41, v16
	v_sub_f32_e32 v98, v98, v16
	v_sub_f32_e32 v99, v99, v16
	v_sub_f32_e32 v100, v100, v16
	v_sub_f32_e32 v22, v22, v16
	v_sub_f32_e32 v101, v101, v16
	v_sub_f32_e32 v16, v23, v16
	v_mul_f32_e32 v23, 0x4b800000, v19
	v_cmp_gt_f32_e64 s[0:1], s46, v19
	v_cmp_gt_f32_e64 s[6:7], s46, v91
	v_sub_f32_e32 v86, v86, v18
	v_sub_f32_e32 v24, v24, v18
	v_sub_f32_e32 v87, v87, v18
	v_sub_f32_e32 v25, v25, v18
	v_sub_f32_e32 v102, v102, v18
	v_sub_f32_e32 v26, v26, v18
	v_sub_f32_e32 v103, v103, v18
	v_sub_f32_e32 v18, v27, v18
	v_mul_f32_e32 v27, 0x4b800000, v21
	v_cmp_gt_f32_e64 s[4:5], s46, v21
	v_sub_f32_e32 v88, v88, v20
	v_sub_f32_e32 v28, v28, v20
	v_sub_f32_e32 v89, v89, v20
	v_sub_f32_e32 v29, v29, v20
	v_sub_f32_e32 v104, v104, v20
	v_sub_f32_e32 v30, v30, v20
	v_sub_f32_e32 v105, v105, v20
	v_sub_f32_e32 v20, v31, v20
	v_cndmask_b32_e64 v31, v91, v106, s[6:7]
	v_cndmask_b32_e32 v17, v17, v97, vcc
	v_cndmask_b32_e64 v19, v19, v23, s[0:1]
	v_cndmask_b32_e64 v21, v21, v27, s[4:5]
	v_rsq_f32_e32 v23, v31
	v_rsq_f32_e32 v17, v17
	v_rsq_f32_e32 v19, v19
	v_rsq_f32_e32 v21, v21
	v_mul_f32_e32 v27, 0x45800000, v23
	v_mul_f32_e32 v31, 0x45800000, v17
	v_mul_f32_e32 v91, 0x45800000, v19
	v_mul_f32_e32 v97, 0x45800000, v21
	v_cndmask_b32_e64 v23, v23, v27, s[6:7]
	v_cndmask_b32_e32 v17, v17, v31, vcc
; #define LAS __attribute__((address_space(3)))
; __device__ __forceinline__ void phase_mix0(const Params& p, LAS unsigned char* lds) {
;     ...
;             for (int e = 0; e < 8; ++e) vnT[(d8 + e) * 136 + ((((j >> 3) ^ (pc & 15)) << 3) | (j & 7))] = (h16)(((float)v[e] - mu) * rs * lng[g * 128 + d8 + e] + lnb[g * 128 + d8 + e]); }
;         __syncthreads();
;         const int itile = wave >> 1, dt0 = (wave & 1) * 2;
;         f32x16 acc0, acc1;
; #pragma unroll
;         for (int e = 0; e < 16; ++e) { acc0[e] = 0.f; acc1[e] = 0.f; }
;         const h16* Arow = WSH + ((size_t)g * 128 + itile * 32 + (lane & 31)) * 128 + 8 * (lane >> 5);
;         const int d0_ = dt0 * 32 + (lane & 31), d1_ = d0_ + 32;
;         const LAS h16* B0p = vnT + d0_ * 136; const LAS h16* B1p = vnT + d1_ * 136;
; #pragma unroll
;         for (int ks = 0; ks < 8; ++ks) {
;             const h16x8 a = *(const h16x8*)(Arow + 16 * ks);
;             const int jg = 2 * ks + (lane >> 5);
;             const h16x8 b0 = *(const LAS h16x8*)(B0p + ((jg ^ ((d0_ >> 3) & 15)) << 3)), b1 = *(const LAS h16x8*)(B1p + ((jg ^ ((d1_ >> 3) & 15)) << 3));
;             acc0 = __builtin_amdgcn_mfma_f32_32x32x16_f16(a, b0, acc0, 0, 0, 0);
;             acc1 = __builtin_amdgcn_mfma_f32_32x32x16_f16(a, b1, acc1, 0, 0, 0);
;         }
	v_cndmask_b32_e64 v19, v19, v91, s[0:1]
	v_cndmask_b32_e64 v21, v21, v97, s[4:5]
	v_mul_f32_e32 v27, v32, v23
	v_mul_f32_e32 v31, v85, v23
	v_mul_f32_e32 v32, v92, v23
	v_mul_f32_e32 v85, v93, v23
	v_mul_f32_e32 v91, v94, v23
	v_mul_f32_e32 v92, v95, v23
	v_mul_f32_e32 v93, v96, v23
	v_mul_f32_e32 v23, v90, v23
	v_mul_f32_e32 v40, v40, v17
	v_mul_f32_e32 v41, v41, v17
	v_mul_f32_e32 v90, v98, v17
	v_mul_f32_e32 v94, v99, v17
	v_mul_f32_e32 v95, v100, v17
	v_mul_f32_e32 v22, v22, v17
	v_mul_f32_e32 v96, v101, v17
	v_mul_f32_e32 v16, v16, v17
	v_mul_f32_e32 v17, v86, v19
	v_mul_f32_e32 v86, v87, v19
	v_mul_f32_e32 v87, v102, v19
	v_mul_f32_e32 v18, v18, v19
	v_mul_f32_e32 v24, v24, v19
	v_mul_f32_e32 v25, v25, v19
	v_mul_f32_e32 v26, v26, v19
	v_mul_f32_e32 v97, v103, v19
	v_mul_f32_e32 v19, v88, v21
	v_mul_f32_e32 v28, v28, v21
	v_mul_f32_e32 v88, v89, v21
	v_mul_f32_e32 v29, v29, v21
	v_mul_f32_e32 v89, v104, v21
	v_mul_f32_e32 v30, v30, v21
	v_mul_f32_e32 v98, v105, v21
	v_mul_f32_e32 v20, v20, v21
	v_fma_mixlo_f16 v21, v8, v27, v12
	v_fma_mixlo_f16 v16, v3, v16, v7
	v_fma_mixlo_f16 v17, v8, v17, v12
	v_fma_mixlo_f16 v86, v10, v86, v14
	v_fma_mixlo_f16 v87, v0, v87, v4
	v_fma_mixlo_f16 v18, v3, v18, v7
	v_fma_mixlo_f16 v27, v9, v31, v13
	v_fma_mixlo_f16 v31, v10, v32, v14
	v_fma_mixlo_f16 v32, v85, v11, v15
	v_fma_mixlo_f16 v85, v91, v0, v4
	v_fma_mixlo_f16 v91, v92, v1, v5
	v_fma_mixlo_f16 v92, v93, v2, v6
	v_fma_mixlo_f16 v23, v23, v3, v7
	v_fma_mixlo_f16 v40, v8, v40, v12
	v_fma_mixlo_f16 v41, v9, v41, v13
	v_fma_mixlo_f16 v90, v10, v90, v14
	v_fma_mixlo_f16 v93, v11, v94, v15
	v_fma_mixlo_f16 v94, v0, v95, v4
	v_fma_mixlo_f16 v22, v1, v22, v5
	v_fma_mixlo_f16 v95, v2, v96, v6
	v_fma_mixlo_f16 v24, v9, v24, v13
	v_fma_mixlo_f16 v25, v11, v25, v15
	v_fma_mixlo_f16 v26, v1, v26, v5
	v_fma_mixlo_f16 v96, v2, v97, v6
	v_fma_mixlo_f16 v8, v8, v19, v12
	v_fma_mixlo_f16 v9, v9, v28, v13
	v_fma_mixlo_f16 v10, v10, v88, v14
	v_fma_mixlo_f16 v11, v11, v29, v15
	v_fma_mixlo_f16 v0, v0, v89, v4
	v_fma_mixlo_f16 v1, v1, v30, v5
	v_fma_mixlo_f16 v2, v2, v98, v6
	v_fma_mixlo_f16 v3, v3, v20, v7
	ds_write_b16 v81, v21
	ds_write_b16 v81, v27 offset:272
	ds_write_b16 v81, v31 offset:544
	ds_write_b16 v81, v32 offset:816
	ds_write_b16 v81, v85 offset:1088
	ds_write_b16 v81, v91 offset:1360
	ds_write_b16 v81, v92 offset:1632
	ds_write_b16 v81, v23 offset:1904
	ds_write_b16 v82, v40
	ds_write_b16 v82, v41 offset:272
	ds_write_b16 v82, v90 offset:544
	ds_write_b16 v82, v93 offset:816
	ds_write_b16 v82, v94 offset:1088
	ds_write_b16 v82, v22 offset:1360
	ds_write_b16 v82, v95 offset:1632
	ds_write_b16 v82, v16 offset:1904
	ds_write_b16 v83, v17
	ds_write_b16 v83, v24 offset:272
	ds_write_b16 v83, v86 offset:544
	ds_write_b16 v83, v25 offset:816
	ds_write_b16 v83, v87 offset:1088
	ds_write_b16 v83, v26 offset:1360
	ds_write_b16 v83, v96 offset:1632
	ds_write_b16 v83, v18 offset:1904
	ds_write_b16 v84, v8
	ds_write_b16 v84, v9 offset:272
	ds_write_b16 v84, v10 offset:544
	ds_write_b16 v84, v11 offset:816
	ds_write_b16 v84, v0 offset:1088
	ds_write_b16 v84, v1 offset:1360
	ds_write_b16 v84, v2 offset:1632
	ds_write_b16 v84, v3 offset:1904
	s_waitcnt lgkmcnt(0)
	s_barrier
	ds_read_b128 v[0:3], v50
	ds_read_b128 v[20:23], v51
	ds_read_b128 v[90:93], v52
	ds_read_b128 v[94:97], v53
	s_waitcnt vmcnt(36) lgkmcnt(3)
	v_mfma_f32_32x32x16_f16 v[0:15], v[132:135], v[0:3], 0
	s_waitcnt lgkmcnt(2)
	v_mfma_f32_32x32x16_f16 v[16:31], v[132:135], v[20:23], 0
	ds_read_b128 v[98:101], v54
	ds_read_b128 v[102:105], v55
	s_waitcnt lgkmcnt(3)
	v_mfma_f32_32x32x16_f16 v[0:15], v[136:139], v[90:93], v[0:15]
	s_waitcnt lgkmcnt(2)
	v_mfma_f32_32x32x16_f16 v[16:31], v[136:139], v[94:97], v[16:31]
	ds_read_b128 v[90:93], v56
	ds_read_b128 v[94:97], v57
	s_waitcnt lgkmcnt(3)
	v_mfma_f32_32x32x16_f16 v[0:15], v[140:143], v[98:101], v[0:15]
	s_waitcnt lgkmcnt(2)
	v_mfma_f32_32x32x16_f16 v[16:31], v[140:143], v[102:105], v[16:31]
	ds_read_b128 v[98:101], v58
	ds_read_b128 v[102:105], v59
	s_waitcnt lgkmcnt(3)
	v_mfma_f32_32x32x16_f16 v[0:15], v[144:147], v[90:93], v[0:15]
	s_waitcnt lgkmcnt(2)
	v_mfma_f32_32x32x16_f16 v[16:31], v[144:147], v[94:97], v[16:31]
	ds_read_b128 v[90:93], v60
	ds_read_b128 v[94:97], v61
	s_waitcnt lgkmcnt(3)
	v_mfma_f32_32x32x16_f16 v[0:15], v[148:151], v[98:101], v[0:15]
	s_waitcnt lgkmcnt(2)
	v_mfma_f32_32x32x16_f16 v[16:31], v[148:151], v[102:105], v[16:31]
	ds_read_b128 v[98:101], v62
	ds_read_b128 v[102:105], v63
	s_waitcnt lgkmcnt(3)
	v_mfma_f32_32x32x16_f16 v[0:15], v[152:155], v[90:93], v[0:15]
	s_waitcnt lgkmcnt(2)
	v_mfma_f32_32x32x16_f16 v[16:31], v[152:155], v[94:97], v[16:31]
	ds_read_b128 v[90:93], v64
	ds_read_b128 v[94:97], v65
	s_waitcnt lgkmcnt(3)
	v_mfma_f32_32x32x16_f16 v[0:15], v[156:159], v[98:101], v[0:15]
	s_waitcnt lgkmcnt(2)
	v_mfma_f32_32x32x16_f16 v[16:31], v[156:159], v[102:105], v[16:31]
	s_waitcnt lgkmcnt(1)
	v_mfma_f32_32x32x16_f16 v[0:15], v[160:163], v[90:93], v[0:15]
	s_waitcnt lgkmcnt(0)
	v_mfma_f32_32x32x16_f16 v[16:31], v[160:163], v[94:97], v[16:31]
	s_add_i32 s23, s23, s28
	v_or_b32_e32 v202, s14, v44
	v_lshlrev_b32_e32 v202, 1, v202
	v_mov_b32_e32 v203, 0
	v_lshl_add_u64 v[204:205], s[10:11], 0, v[202:203]
	s_waitcnt vmcnt(0)
; __device__ __forceinline__ void phase_mix0(const Params& p, LAS unsigned char* lds) {
;     ...
;         for (int r = 0; r < 16; ++r) { const int i = itile * 32 + (r & 3) + 8 * (r >> 2) + 4 * (lane >> 5); const size_t t = (size_t)(t0 + i);
;             const float bias = bs[g * 128 + i];
;             const int d0 = g * 128 + dt0 * 32 + (lane & 31);
;             YC[t * 2048 + 1024 + d0] = (h16)((acc0[r] + bias) * (float)U[t * 1024 + d0]);
;             YC[t * 2048 + 1024 + d0 + 32] = (h16)((acc1[r] + bias) * (float)U[t * 1024 + d0 + 32]); }
	s_nop 7
	s_nop 7
	s_nop 7
	v_add_f32_e32 v214, v0, v110
	v_add_f32_e32 v215, v16, v110
	v_add_u32_e32 v206, s48, v45
	v_ashrrev_i32_e32 v207, 31, v206
	v_fma_mixlo_f16 v214, v214, v170, 0 op_sel_hi:[0,1,0]
	v_fma_mixlo_f16 v215, v215, v171, 0 op_sel_hi:[0,1,0]
	v_lshlrev_b64 v[208:209], 12, v[206:207]
	v_lshl_add_u64 v[208:209], v[204:205], 0, v[208:209]
	global_store_short v[208:209], v214, off offset:2048
	global_store_short v[208:209], v215, off offset:2112
	v_add_f32_e32 v216, v1, v111
	v_add_f32_e32 v217, v17, v111
	v_add_u32_e32 v210, s48, v66
	v_ashrrev_i32_e32 v211, 31, v210
	v_fma_mixlo_f16 v216, v216, v172, 0 op_sel_hi:[0,1,0]
	v_fma_mixlo_f16 v217, v217, v173, 0 op_sel_hi:[0,1,0]
	v_lshlrev_b64 v[212:213], 12, v[210:211]
	v_lshl_add_u64 v[212:213], v[204:205], 0, v[212:213]
	global_store_short v[212:213], v216, off offset:2048
	global_store_short v[212:213], v217, off offset:2112
	v_add_f32_e32 v214, v2, v112
	v_add_f32_e32 v215, v18, v112
	v_add_u32_e32 v206, s48, v67
	v_ashrrev_i32_e32 v207, 31, v206
	v_fma_mixlo_f16 v214, v214, v174, 0 op_sel_hi:[0,1,0]
	v_fma_mixlo_f16 v215, v215, v175, 0 op_sel_hi:[0,1,0]
	v_lshlrev_b64 v[208:209], 12, v[206:207]
	v_lshl_add_u64 v[208:209], v[204:205], 0, v[208:209]
	global_store_short v[208:209], v214, off offset:2048
	global_store_short v[208:209], v215, off offset:2112
	v_add_f32_e32 v216, v3, v113
	v_add_f32_e32 v217, v19, v113
	v_add_u32_e32 v210, s48, v68
	v_ashrrev_i32_e32 v211, 31, v210
	v_fma_mixlo_f16 v216, v216, v176, 0 op_sel_hi:[0,1,0]
	v_fma_mixlo_f16 v217, v217, v177, 0 op_sel_hi:[0,1,0]
	v_lshlrev_b64 v[212:213], 12, v[210:211]
	v_lshl_add_u64 v[212:213], v[204:205], 0, v[212:213]
	global_store_short v[212:213], v216, off offset:2048
	global_store_short v[212:213], v217, off offset:2112
	v_add_f32_e32 v214, v4, v114
	v_add_f32_e32 v215, v20, v114
	v_add_u32_e32 v206, s48, v69
	v_ashrrev_i32_e32 v207, 31, v206
	v_fma_mixlo_f16 v214, v214, v178, 0 op_sel_hi:[0,1,0]
	v_fma_mixlo_f16 v215, v215, v179, 0 op_sel_hi:[0,1,0]
	v_lshlrev_b64 v[208:209], 12, v[206:207]
	v_lshl_add_u64 v[208:209], v[204:205], 0, v[208:209]
	global_store_short v[208:209], v214, off offset:2048
	global_store_short v[208:209], v215, off offset:2112
	v_add_f32_e32 v216, v5, v115
	v_add_f32_e32 v217, v21, v115
	v_add_u32_e32 v210, s48, v70
	v_ashrrev_i32_e32 v211, 31, v210
	v_fma_mixlo_f16 v216, v216, v180, 0 op_sel_hi:[0,1,0]
	v_fma_mixlo_f16 v217, v217, v181, 0 op_sel_hi:[0,1,0]
	v_lshlrev_b64 v[212:213], 12, v[210:211]
	v_lshl_add_u64 v[212:213], v[204:205], 0, v[212:213]
	global_store_short v[212:213], v216, off offset:2048
	global_store_short v[212:213], v217, off offset:2112
	v_add_f32_e32 v214, v6, v116
	v_add_f32_e32 v215, v22, v116
	v_add_u32_e32 v206, s48, v71
	v_ashrrev_i32_e32 v207, 31, v206
	v_fma_mixlo_f16 v214, v214, v182, 0 op_sel_hi:[0,1,0]
	v_fma_mixlo_f16 v215, v215, v183, 0 op_sel_hi:[0,1,0]
	v_lshlrev_b64 v[208:209], 12, v[206:207]
	v_lshl_add_u64 v[208:209], v[204:205], 0, v[208:209]
	global_store_short v[208:209], v214, off offset:2048
	global_store_short v[208:209], v215, off offset:2112
	v_add_f32_e32 v216, v7, v117
	v_add_f32_e32 v217, v23, v117
	v_add_u32_e32 v210, s48, v72
	v_ashrrev_i32_e32 v211, 31, v210
	v_fma_mixlo_f16 v216, v216, v184, 0 op_sel_hi:[0,1,0]
	v_fma_mixlo_f16 v217, v217, v185, 0 op_sel_hi:[0,1,0]
	v_lshlrev_b64 v[212:213], 12, v[210:211]
	v_lshl_add_u64 v[212:213], v[204:205], 0, v[212:213]
	global_store_short v[212:213], v216, off offset:2048
	global_store_short v[212:213], v217, off offset:2112
; __device__ __forceinline__ void phase_mix0(const Params& p, LAS unsigned char* lds) {
;     ...
;         for (int r = 0; r < 16; ++r) { const int i = itile * 32 + (r & 3) + 8 * (r >> 2) + 4 * (lane >> 5); const size_t t = (size_t)(t0 + i);
;             const float bias = bs[g * 128 + i];
;             const int d0 = g * 128 + dt0 * 32 + (lane & 31);
;             YC[t * 2048 + 1024 + d0] = (h16)((acc0[r] + bias) * (float)U[t * 1024 + d0]);
;             YC[t * 2048 + 1024 + d0 + 32] = (h16)((acc1[r] + bias) * (float)U[t * 1024 + d0 + 32]); }
;     }
	v_add_f32_e32 v214, v8, v118
	v_add_f32_e32 v215, v24, v118
	v_add_u32_e32 v206, s48, v73
	v_ashrrev_i32_e32 v207, 31, v206
	v_fma_mixlo_f16 v214, v214, v186, 0 op_sel_hi:[0,1,0]
	v_fma_mixlo_f16 v215, v215, v187, 0 op_sel_hi:[0,1,0]
	v_lshlrev_b64 v[208:209], 12, v[206:207]
	v_lshl_add_u64 v[208:209], v[204:205], 0, v[208:209]
	global_store_short v[208:209], v214, off offset:2048
	global_store_short v[208:209], v215, off offset:2112
	v_add_f32_e32 v216, v9, v119
	v_add_f32_e32 v217, v25, v119
	v_add_u32_e32 v210, s48, v74
	v_ashrrev_i32_e32 v211, 31, v210
	v_fma_mixlo_f16 v216, v216, v188, 0 op_sel_hi:[0,1,0]
	v_fma_mixlo_f16 v217, v217, v189, 0 op_sel_hi:[0,1,0]
	v_lshlrev_b64 v[212:213], 12, v[210:211]
	v_lshl_add_u64 v[212:213], v[204:205], 0, v[212:213]
	global_store_short v[212:213], v216, off offset:2048
	global_store_short v[212:213], v217, off offset:2112
	v_add_f32_e32 v214, v10, v120
	v_add_f32_e32 v215, v26, v120
	v_add_u32_e32 v206, s48, v75
	v_ashrrev_i32_e32 v207, 31, v206
	v_fma_mixlo_f16 v214, v214, v190, 0 op_sel_hi:[0,1,0]
	v_fma_mixlo_f16 v215, v215, v191, 0 op_sel_hi:[0,1,0]
	v_lshlrev_b64 v[208:209], 12, v[206:207]
	v_lshl_add_u64 v[208:209], v[204:205], 0, v[208:209]
	global_store_short v[208:209], v214, off offset:2048
	global_store_short v[208:209], v215, off offset:2112
	v_add_f32_e32 v216, v11, v121
	v_add_f32_e32 v217, v27, v121
	v_add_u32_e32 v210, s48, v76
	v_ashrrev_i32_e32 v211, 31, v210
	v_fma_mixlo_f16 v216, v216, v192, 0 op_sel_hi:[0,1,0]
	v_fma_mixlo_f16 v217, v217, v193, 0 op_sel_hi:[0,1,0]
	v_lshlrev_b64 v[212:213], 12, v[210:211]
	v_lshl_add_u64 v[212:213], v[204:205], 0, v[212:213]
	global_store_short v[212:213], v216, off offset:2048
	global_store_short v[212:213], v217, off offset:2112
	v_add_f32_e32 v214, v12, v122
	v_add_f32_e32 v215, v28, v122
	v_add_u32_e32 v206, s48, v77
	v_ashrrev_i32_e32 v207, 31, v206
	v_fma_mixlo_f16 v214, v214, v194, 0 op_sel_hi:[0,1,0]
	v_fma_mixlo_f16 v215, v215, v195, 0 op_sel_hi:[0,1,0]
	v_lshlrev_b64 v[208:209], 12, v[206:207]
	v_lshl_add_u64 v[208:209], v[204:205], 0, v[208:209]
	global_store_short v[208:209], v214, off offset:2048
	global_store_short v[208:209], v215, off offset:2112
	v_add_f32_e32 v216, v13, v123
	v_add_f32_e32 v217, v29, v123
	v_add_u32_e32 v210, s48, v78
	v_ashrrev_i32_e32 v211, 31, v210
	v_fma_mixlo_f16 v216, v216, v196, 0 op_sel_hi:[0,1,0]
	v_fma_mixlo_f16 v217, v217, v197, 0 op_sel_hi:[0,1,0]
	v_lshlrev_b64 v[212:213], 12, v[210:211]
	v_lshl_add_u64 v[212:213], v[204:205], 0, v[212:213]
	global_store_short v[212:213], v216, off offset:2048
	global_store_short v[212:213], v217, off offset:2112
	v_add_f32_e32 v214, v14, v124
	v_add_f32_e32 v215, v30, v124
	v_add_u32_e32 v206, s48, v79
	v_ashrrev_i32_e32 v207, 31, v206
	v_fma_mixlo_f16 v214, v214, v198, 0 op_sel_hi:[0,1,0]
	v_fma_mixlo_f16 v215, v215, v199, 0 op_sel_hi:[0,1,0]
	v_lshlrev_b64 v[208:209], 12, v[206:207]
	v_lshl_add_u64 v[208:209], v[204:205], 0, v[208:209]
	global_store_short v[208:209], v214, off offset:2048
	global_store_short v[208:209], v215, off offset:2112
	v_add_f32_e32 v216, v15, v125
	v_add_f32_e32 v217, v31, v125
	v_add_u32_e32 v210, s48, v80
	v_ashrrev_i32_e32 v211, 31, v210
	v_fma_mixlo_f16 v216, v216, v200, 0 op_sel_hi:[0,1,0]
	v_fma_mixlo_f16 v217, v217, v201, 0 op_sel_hi:[0,1,0]
	v_lshlrev_b64 v[212:213], 12, v[210:211]
	v_lshl_add_u64 v[212:213], v[204:205], 0, v[212:213]
	global_store_short v[212:213], v216, off offset:2048
	global_store_short v[212:213], v217, off offset:2112
	s_cmpk_lt_i32 s47, 0x400
	s_cbranch_scc1 .LBB0_289
